# attention prologue: Q rows via 4 coalesced LDS-DMA per wave into the idle O stage, fragments read once from LDS and reused for the q-norm bound and the QK MFMAs (were 2x4 row-per-lane global loads)
# baseline (speedup 1.0000x reference)
.LBB0_137:
	s_or_b64 exec, exec, s[12:13]
	s_ashr_i32 s16, s20, 6
	s_sub_i32 s19, 15, s16
	s_lshr_b32 s15, s18, 4
	s_lshl_b32 s17, s15, 12
	s_lshl_b32 s14, s19, 8
	s_add_u32 s2, s17, s14
	s_addc_u32 s3, 0, 0
	v_and_b32_e32 v30, 0xffffffe0, v202
	v_lshrrev_b32_e32 v31, 3, v244
	v_or_b32_e32 v30, v30, v31
	v_mov_b32_e32 v31, 0
	v_lshl_add_u64 v[10:11], s[2:3], 0, v[30:31]
	v_readlane_b32 s2, v252, 23
	v_lshlrev_b64 v[10:11], 11, v[10:11]
	v_readlane_b32 s3, v252, 24
	s_mov_b32 s13, s79
	v_and_b32_e32 v30, 7, v244
	v_lshl_add_u64 v[10:11], s[2:3], 0, v[10:11]
	s_lshl_b32 s2, s20, 6
	s_and_b32 s2, s2, 0x3c0
	s_lshl_b32 s12, s2, 1
	v_lshlrev_b32_e32 v30, 4, v30
	v_lshl_add_u64 v[10:11], v[10:11], 0, s[12:13]
	v_readfirstlane_b32 s32, v200
	v_lshl_add_u64 v[10:11], v[10:11], 0, v[30:31]
	s_mov_b64 s[100:101], 0x4000
	s_lshr_b32 s32, s32, 6
	s_lshl_b32 s32, s32, 12
	s_add_i32 m0, s32, 0xc800
	s_nop 0
	global_load_lds_dwordx4 v[10:11], off
	v_lshl_add_u64 v[10:11], v[10:11], 0, s[100:101]
	s_add_i32 m0, s32, 0xcc00
	s_nop 0
	global_load_lds_dwordx4 v[10:11], off
	v_lshl_add_u64 v[10:11], v[10:11], 0, s[100:101]
	s_add_i32 m0, s32, 0xd000
	s_nop 0
	global_load_lds_dwordx4 v[10:11], off
	v_lshl_add_u64 v[10:11], v[10:11], 0, s[100:101]
	s_add_i32 m0, s32, 0xd400
	s_nop 0
	global_load_lds_dwordx4 v[10:11], off
	s_lshl_b32 s2, s18, 3
	v_mov_b32_e32 v30, s2
	global_load_dwordx2 v[34:35], v30, s[10:11]
	v_cmp_lt_i32_e64 s[2:3], v237, v231
	s_waitcnt vmcnt(0)
	v_lshlrev_b32_e32 v30, 7, v202
	v_add_u32_e32 v30, v30, v192
	ds_read_b128 v[14:17], v30 offset:51200
	ds_read_b128 v[18:21], v30 offset:51232
	ds_read_b128 v[22:25], v30 offset:51264
	ds_read_b128 v[26:29], v30 offset:51296
	s_waitcnt lgkmcnt(0)
	v_and_b32_e32 v31, 0xffff0000, v14
	v_lshlrev_b32_e32 v30, 16, v14
	v_mul_f32_e32 v31, v31, v31
	v_fmac_f32_e32 v31, v30, v30
	v_and_b32_e32 v13, 0xffff0000, v15
	v_lshlrev_b32_e32 v30, 16, v15
	v_mul_f32_e32 v13, v13, v13
	v_fmac_f32_e32 v13, v30, v30
	v_add_f32_e32 v9, v31, v13
	v_and_b32_e32 v13, 0xffff0000, v16
	v_lshlrev_b32_e32 v30, 16, v16
	v_mul_f32_e32 v13, v13, v13
	v_fmac_f32_e32 v13, v30, v30
	v_add_f32_e32 v9, v13, v9
	v_and_b32_e32 v13, 0xffff0000, v17
	v_lshlrev_b32_e32 v30, 16, v17
	v_mul_f32_e32 v13, v13, v13
	v_fmac_f32_e32 v13, v30, v30
	v_add_f32_e32 v9, v13, v9
	v_and_b32_e32 v13, 0xffff0000, v18
	v_lshlrev_b32_e32 v30, 16, v18
	v_mul_f32_e32 v13, v13, v13
	v_fmac_f32_e32 v13, v30, v30
	v_add_f32_e32 v9, v13, v9
	v_and_b32_e32 v13, 0xffff0000, v19
	v_lshlrev_b32_e32 v30, 16, v19
	v_mul_f32_e32 v13, v13, v13
	v_fmac_f32_e32 v13, v30, v30
	v_add_f32_e32 v9, v13, v9
	v_and_b32_e32 v13, 0xffff0000, v20
	v_lshlrev_b32_e32 v30, 16, v20
	v_mul_f32_e32 v13, v13, v13
	v_fmac_f32_e32 v13, v30, v30
	v_add_f32_e32 v9, v13, v9
	v_and_b32_e32 v13, 0xffff0000, v21
	v_lshlrev_b32_e32 v30, 16, v21
	v_mul_f32_e32 v13, v13, v13
	v_fmac_f32_e32 v13, v30, v30
	v_add_f32_e32 v9, v13, v9
	v_and_b32_e32 v13, 0xffff0000, v22
	v_lshlrev_b32_e32 v30, 16, v22
	v_mul_f32_e32 v13, v13, v13
	v_fmac_f32_e32 v13, v30, v30
	v_add_f32_e32 v9, v13, v9
	v_and_b32_e32 v13, 0xffff0000, v23
	v_lshlrev_b32_e32 v30, 16, v23
	v_mul_f32_e32 v13, v13, v13
	v_fmac_f32_e32 v13, v30, v30
	v_add_f32_e32 v9, v13, v9
	v_and_b32_e32 v13, 0xffff0000, v24
	v_lshlrev_b32_e32 v30, 16, v24
	v_mul_f32_e32 v13, v13, v13
	v_fmac_f32_e32 v13, v30, v30
	v_add_f32_e32 v9, v13, v9
	v_and_b32_e32 v13, 0xffff0000, v25
	v_lshlrev_b32_e32 v30, 16, v25
	v_mul_f32_e32 v13, v13, v13
	v_fmac_f32_e32 v13, v30, v30
	v_add_f32_e32 v9, v13, v9
	v_and_b32_e32 v13, 0xffff0000, v26
	v_lshlrev_b32_e32 v30, 16, v26
	v_mul_f32_e32 v13, v13, v13
	v_fmac_f32_e32 v13, v30, v30
	v_add_f32_e32 v9, v13, v9
	v_and_b32_e32 v13, 0xffff0000, v27
	v_lshlrev_b32_e32 v30, 16, v27
	v_mul_f32_e32 v13, v13, v13
	v_fmac_f32_e32 v13, v30, v30
	v_add_f32_e32 v9, v13, v9
	v_and_b32_e32 v13, 0xffff0000, v28
	v_lshlrev_b32_e32 v30, 16, v28
	v_mul_f32_e32 v13, v13, v13
	v_fmac_f32_e32 v13, v30, v30
	v_add_f32_e32 v9, v13, v9
	v_and_b32_e32 v13, 0xffff0000, v29
	v_lshlrev_b32_e32 v30, 16, v29
	v_mul_f32_e32 v13, v13, v13
	v_fmac_f32_e32 v13, v30, v30
	v_add_f32_e32 v9, v13, v9
	v_cndmask_b32_e64 v10, v228, v237, s[2:3]
	v_lshlrev_b32_e32 v10, 2, v10
	ds_bpermute_b32 v10, v10, v9
	v_cmp_lt_i32_e64 s[2:3], v232, v231
	s_waitcnt lgkmcnt(0)
	v_add_f32_e32 v9, v9, v10
	v_cndmask_b32_e64 v10, v228, v232, s[2:3]
	v_lshlrev_b32_e32 v10, 2, v10
	ds_bpermute_b32 v10, v10, v9
	v_cmp_lt_i32_e64 s[2:3], v233, v231
	s_waitcnt lgkmcnt(0)
	v_max_f32_e32 v10, v10, v10
	v_max_f32_e32 v9, v9, v10
	v_cndmask_b32_e64 v10, v228, v233, s[2:3]
	v_lshlrev_b32_e32 v10, 2, v10
	ds_bpermute_b32 v10, v10, v9
	v_cmp_lt_i32_e64 s[2:3], v234, v231
	s_waitcnt lgkmcnt(0)
	v_max_f32_e32 v10, v10, v10
	v_max_f32_e32 v9, v9, v10
	v_cndmask_b32_e64 v10, v228, v234, s[2:3]
	v_lshlrev_b32_e32 v10, 2, v10
	ds_bpermute_b32 v10, v10, v9
	v_cmp_lt_i32_e64 s[2:3], v235, v231
	s_waitcnt lgkmcnt(0)
	v_max_f32_e32 v10, v10, v10
	v_max_f32_e32 v9, v9, v10
	v_cndmask_b32_e64 v10, v228, v235, s[2:3]
	v_lshlrev_b32_e32 v10, 2, v10
	ds_bpermute_b32 v10, v10, v9
	v_cmp_lt_i32_e64 s[2:3], v236, v231
	s_waitcnt lgkmcnt(0)
	v_max_f32_e32 v10, v10, v10
	v_max_f32_e32 v9, v9, v10
	v_cndmask_b32_e64 v10, v228, v236, s[2:3]
	v_lshlrev_b32_e32 v10, 2, v10
	ds_bpermute_b32 v10, v10, v9
	s_and_saveexec_b64 s[2:3], s[6:7]
	s_cbranch_execnz .LBB0_162
	s_or_b64 exec, exec, s[2:3]
	s_and_saveexec_b64 s[2:3], s[4:5]
	s_cbranch_execnz .LBB0_163

.LBB0_144:
	s_or_b64 exec, exec, s[4:5]
	v_cndmask_b32_e64 v0, 0, 1, s[2:3]
	v_cmp_ne_u32_e32 vcc, 0, v0
	s_not_b64 s[2:3], vcc
	s_ff1_i32_b64 s2, s[2:3]
	v_readfirstlane_b32 s5, v32
	s_min_u32 s2, s2, 64
	s_ashr_i32 s13, s5, 6
	s_and_b32 s2, s2, 0x7e
	s_lshl_b32 s20, s13, 5
	s_min_u32 s40, s2, s6
	s_add_i32 s2, s14, s17
	s_ashr_i32 s3, s20, 31
	s_add_u32 s2, s20, s2
	s_addc_u32 s3, s3, 0
	s_lshl_b64 s[6:7], s[2:3], 11
	v_readlane_b32 s18, v252, 23
	v_readlane_b32 s19, v252, 24
	s_add_u32 s4, s18, s6
	s_addc_u32 s7, s19, s7
	s_add_u32 s6, s4, s12
	s_addc_u32 s7, s7, 0
	s_ashr_i32 s41, s40, 31
	s_lshl_b64 s[18:19], s[40:41], 16
	s_lshl_b32 s4, s15, 22
	s_add_u32 s18, s18, s4
	s_addc_u32 s19, s19, 0
	s_lshl_b64 s[18:19], s[18:19], 1
	s_add_u32 s4, s46, s18
	v_readlane_b32 s15, v252, 32
	s_addc_u32 s15, s15, s19
	s_add_u32 s52, s4, s12
	s_addc_u32 s53, s15, 0
	v_readlane_b32 s4, v252, 33
	s_add_u32 s4, s4, s18
	v_readlane_b32 s15, v252, 34
	v_mov_b32_e32 v0, s68
	v_and_b32_e32 v197, 63, v32
	s_addc_u32 s15, s15, s19
	ds_read_b32 v196, v0
	s_add_u32 s18, s4, s12
	v_lshlrev_b32_e32 v0, 11, v197
	v_mov_b32_e32 v1, v193
	s_addc_u32 s19, s15, 0
	v_lshl_add_u64 v[0:1], s[52:53], 0, v[0:1]
	s_lshl_b32 s52, s13, 3
	s_ashr_i32 s53, s52, 31
	v_lshl_add_u64 v[206:207], s[52:53], 1, v[0:1]
	s_lshl_b32 s4, s13, 4
	v_bfe_u32 v0, v32, 2, 4
	v_and_or_b32 v0, s4, 48, v0
	v_lshlrev_b32_e32 v0, 11, v0
	v_mov_b32_e32 v1, v193
	s_ashr_i32 s4, s5, 3
	v_lshl_add_u64 v[0:1], s[18:19], 0, v[0:1]
	s_and_b32 s18, s4, 0xffffffe0
	s_ashr_i32 s19, s18, 31
	s_lshl_b32 s4, s13, 10
	v_lshlrev_b32_e32 v210, 3, v32
	s_cmp_lg_u32 0, -1
	v_and_b32_e32 v213, 24, v210
	s_cselect_b32 s15, 0, 0
	v_bfe_u32 v212, v32, 5, 1
	v_lshl_add_u64 v[0:1], s[18:19], 1, v[0:1]
	v_lshlrev_b32_e32 v2, 1, v213
	v_mov_b32_e32 v3, v193
	s_add_i32 s18, s4, s15
	s_mov_b32 s15, m0
	s_mov_b32 m0, s18
	s_nop 0
	global_load_lds_dwordx4 v[206:207], off
	s_mov_b32 m0, s15
	s_mov_b64 s[22:23], 0x20000
	v_and_b32_e32 v211, 31, v32
	v_lshl_add_u64 v[208:209], v[0:1], 0, v[2:3]
	s_add_i32 s19, s18, 0x6000
	s_mov_b32 s15, m0
	s_mov_b32 m0, s19
	s_nop 0
	global_load_lds_dwordx4 v[208:209], off
	s_mov_b32 m0, s15
	v_lshl_add_u64 v[0:1], v[206:207], 0, s[22:23]
	v_lshlrev_b32_e32 v2, 4, v212
	s_add_i32 s15, s18, 0x2000
	s_mov_b32 s17, m0
	s_mov_b32 m0, s15
	s_nop 0
	global_load_lds_dwordx4 v[0:1], off
	s_mov_b32 m0, s17
	v_lshl_or_b32 v0, v211, 11, v2
	v_mov_b32_e32 v116, v14
	v_mov_b32_e32 v117, v15
	v_mov_b32_e32 v118, v16
	v_mov_b32_e32 v119, v17
	v_mov_b32_e32 v108, v18
	v_mov_b32_e32 v109, v19
	v_mov_b32_e32 v110, v20
	v_mov_b32_e32 v111, v21
	v_mov_b32_e32 v100, v22
	v_mov_b32_e32 v101, v23
	v_mov_b32_e32 v102, v24
	v_mov_b32_e32 v103, v25
	v_mov_b32_e32 v96, v26
	v_mov_b32_e32 v97, v27
	v_mov_b32_e32 v98, v28
	v_mov_b32_e32 v99, v29
	v_lshlrev_b32_e32 v0, 10, v212
	v_lshlrev_b32_e32 v1, 4, v211
	s_add_i32 s6, 0, 0x14800
	v_add3_u32 v220, 0, v0, v1
	v_lshl_add_u64 v[0:1], v[206:207], 0, s[88:89]
	v_add_u32_e32 v2, s6, v2
	s_add_i32 s6, s18, 0x4000
	s_mov_b32 s7, m0
	s_mov_b32 m0, s6
	s_nop 0
	global_load_lds_dwordx4 v[0:1], off
	s_mov_b32 m0, s7
	s_lshl_b32 s17, s40, 8
	s_waitcnt vmcnt(3) lgkmcnt(0)
	s_barrier
	v_add_u32_e32 v33, s17, v2
	ds_read_b128 v[20:23], v220
	ds_read_b128 v[0:3], v33
	ds_read_b128 v[4:7], v33 offset:32
	ds_read_b128 v[8:11], v33 offset:64
	ds_read_b128 v[12:15], v33 offset:96
	ds_read_b128 v[34:37], v220 offset:512
	ds_read_b128 v[16:19], v33 offset:128
	s_addk_i32 s14, 0x100
	s_lshr_b32 s26, s14, 6
	v_or_b32_e32 v219, s20, v211
	s_sub_i32 s20, s26, s40
	v_lshlrev_b32_e32 v218, 2, v212
	s_cmp_gt_i32 s20, 4
	s_waitcnt lgkmcnt(2)
	v_mfma_f32_32x32x16_bf16 v[0:15], v[20:23], v[116:119], v[0:15]
	ds_read_b128 v[20:23], v33 offset:160
	ds_read_b128 v[24:27], v33 offset:192
	ds_read_b128 v[28:31], v33 offset:224
	s_waitcnt lgkmcnt(0)
	v_mfma_f32_32x32x16_bf16 v[16:31], v[34:37], v[116:119], v[16:31]
	ds_read_b128 v[34:37], v220 offset:2048
	s_waitcnt lgkmcnt(0)
	v_mfma_f32_32x32x16_bf16 v[0:15], v[34:37], v[108:111], v[0:15]
	ds_read_b128 v[34:37], v220 offset:2560
	s_waitcnt lgkmcnt(0)
	v_mfma_f32_32x32x16_bf16 v[16:31], v[34:37], v[108:111], v[16:31]
	ds_read_b128 v[34:37], v220 offset:4096
	s_waitcnt lgkmcnt(0)
	v_mfma_f32_32x32x16_bf16 v[0:15], v[34:37], v[100:103], v[0:15]
	ds_read_b128 v[34:37], v220 offset:4608
	s_waitcnt lgkmcnt(0)
	v_mfma_f32_32x32x16_bf16 v[16:31], v[34:37], v[100:103], v[16:31]
	ds_read_b128 v[34:37], v220 offset:6144
	s_waitcnt lgkmcnt(0)
	v_mfma_f32_32x32x16_bf16 v[0:15], v[34:37], v[96:99], v[0:15]
	ds_read_b128 v[34:37], v220 offset:6656
	s_waitcnt lgkmcnt(0)
	v_mfma_f32_32x32x16_bf16 v[16:31], v[34:37], v[96:99], v[16:31]
	s_nop 15
	s_nop 7
	s_cbranch_scc1 .LBB0_146
	s_lshl_b32 s6, s20, 6
	v_subrev_u32_e32 v34, s6, v218
	v_add_u32_e32 v36, 0x120, v34
	v_add_u32_e32 v35, 0x100, v34
	v_cmp_le_i32_e32 vcc, v36, v219
	s_nop 5
	v_cndmask_b32_e32 v16, v238, v16, vcc
	v_cmp_lt_i32_e32 vcc, v35, v219
	s_nop 1
	v_cndmask_b32_e32 v1, v238, v1, vcc
	v_cmp_le_i32_e32 vcc, v35, v219
	v_add_u32_e32 v35, 0x121, v34
	s_nop 0
	v_cndmask_b32_e32 v0, v238, v0, vcc
	v_cmp_le_i32_e32 vcc, v35, v219
	v_add_u32_e32 v35, 0x102, v34
	s_nop 0
	v_cndmask_b32_e32 v17, v238, v17, vcc
	v_cmp_le_i32_e32 vcc, v35, v219
	v_add_u32_e32 v35, 0x122, v34
	s_nop 0
	v_cndmask_b32_e32 v2, v238, v2, vcc
	v_cmp_le_i32_e32 vcc, v35, v219
	v_add_u32_e32 v35, 0x103, v34
	s_nop 0
	v_cndmask_b32_e32 v18, v238, v18, vcc
	v_cmp_le_i32_e32 vcc, v35, v219
	v_add_u32_e32 v35, 0x123, v34
	s_nop 0
	v_cndmask_b32_e32 v3, v238, v3, vcc
	v_cmp_le_i32_e32 vcc, v35, v219
	v_add_u32_e32 v35, 0x108, v34
	s_nop 0
	v_cndmask_b32_e32 v19, v238, v19, vcc
	v_cmp_le_i32_e32 vcc, v35, v219
	v_add_u32_e32 v35, 0x128, v34
	s_nop 0
	v_cndmask_b32_e32 v4, v238, v4, vcc
	v_cmp_le_i32_e32 vcc, v35, v219
	v_add_u32_e32 v35, 0x109, v34
	s_nop 0
	v_cndmask_b32_e32 v20, v238, v20, vcc
	v_cmp_le_i32_e32 vcc, v35, v219
	v_add_u32_e32 v35, 0x129, v34
	s_nop 0
	v_cndmask_b32_e32 v5, v238, v5, vcc
	v_cmp_le_i32_e32 vcc, v35, v219
	v_add_u32_e32 v35, 0x10a, v34
	s_nop 0
	v_cndmask_b32_e32 v21, v238, v21, vcc
	v_cmp_le_i32_e32 vcc, v35, v219
	v_add_u32_e32 v35, 0x12a, v34
	s_nop 0
	v_cndmask_b32_e32 v6, v238, v6, vcc
	v_cmp_le_i32_e32 vcc, v35, v219
	v_add_u32_e32 v35, 0x10b, v34
	s_nop 0
	v_cndmask_b32_e32 v22, v238, v22, vcc
	v_cmp_le_i32_e32 vcc, v35, v219
	v_add_u32_e32 v35, 0x12b, v34
	s_nop 0
	v_cndmask_b32_e32 v7, v238, v7, vcc
	v_cmp_le_i32_e32 vcc, v35, v219
	v_add_u32_e32 v35, 0x110, v34
	s_nop 0
	v_cndmask_b32_e32 v23, v238, v23, vcc
	v_cmp_le_i32_e32 vcc, v35, v219
	v_add_u32_e32 v35, 0x130, v34
	s_nop 0
	v_cndmask_b32_e32 v8, v238, v8, vcc
	v_cmp_le_i32_e32 vcc, v35, v219
	v_add_u32_e32 v35, 0x111, v34
	s_nop 0
	v_cndmask_b32_e32 v24, v238, v24, vcc
	v_cmp_le_i32_e32 vcc, v35, v219
	v_add_u32_e32 v35, 0x131, v34
	s_nop 0
	v_cndmask_b32_e32 v9, v238, v9, vcc
	v_cmp_le_i32_e32 vcc, v35, v219
	v_add_u32_e32 v35, 0x112, v34
	s_nop 0
	v_cndmask_b32_e32 v25, v238, v25, vcc
	v_cmp_le_i32_e32 vcc, v35, v219
	v_add_u32_e32 v35, 0x132, v34
	s_nop 0
	v_cndmask_b32_e32 v10, v238, v10, vcc
	v_cmp_le_i32_e32 vcc, v35, v219
	v_add_u32_e32 v35, 0x113, v34
	s_nop 0
	v_cndmask_b32_e32 v26, v238, v26, vcc
	v_cmp_le_i32_e32 vcc, v35, v219
	v_add_u32_e32 v35, 0x133, v34
	s_nop 0
	v_cndmask_b32_e32 v11, v238, v11, vcc
	v_cmp_le_i32_e32 vcc, v35, v219
	v_add_u32_e32 v35, 0x118, v34
	s_nop 0
	v_cndmask_b32_e32 v27, v238, v27, vcc
	v_cmp_le_i32_e32 vcc, v35, v219
	v_add_u32_e32 v35, 0x138, v34
	s_nop 0
	v_cndmask_b32_e32 v12, v238, v12, vcc
	v_cmp_le_i32_e32 vcc, v35, v219
	v_add_u32_e32 v35, 0x119, v34
	s_nop 0
	v_cndmask_b32_e32 v28, v238, v28, vcc
	v_cmp_le_i32_e32 vcc, v35, v219
	v_add_u32_e32 v35, 0x139, v34
	s_nop 0
	v_cndmask_b32_e32 v13, v238, v13, vcc
	v_cmp_le_i32_e32 vcc, v35, v219
	v_add_u32_e32 v35, 0x11a, v34
	s_nop 0
	v_cndmask_b32_e32 v29, v238, v29, vcc
	v_cmp_le_i32_e32 vcc, v35, v219
	v_add_u32_e32 v35, 0x13a, v34
	s_nop 0
	v_cndmask_b32_e32 v14, v238, v14, vcc
	v_cmp_le_i32_e32 vcc, v35, v219
	v_add_u32_e32 v35, 0x11b, v34
	v_add_u32_e32 v34, 0x13b, v34
	v_cndmask_b32_e32 v30, v238, v30, vcc
	v_cmp_le_i32_e32 vcc, v35, v219
	s_nop 1
	v_cndmask_b32_e32 v15, v238, v15, vcc
	v_cmp_le_i32_e32 vcc, v34, v219
	s_nop 1
	v_cndmask_b32_e32 v31, v238, v31, vcc
